# attention pipeline: LDS buffer select via immediate offsets instead of per-tile address toggles
# baseline (speedup 1.0000x reference)
; __device__ __forceinline__ unsigned pack2(float a, float b) { unsigned r; asm("v_cvt_pk_bf16_f32 %0, %1, %2" : "=v"(r) : "v"(a), "v"(b)); return r; }
; __device__ __forceinline__ void phase_attn(CP& p, char* smem, int vid0, int grid) {
;     ...
;       const float mnew = mrun;
;       float psum = 0.f;
;       bf16x8 pf[4];
; #pragma unroll
;       for (int t2 = 0; t2 < 2; ++t2)
; #pragma unroll
;         for (int hf = 0; hf < 2; ++hf) {
;           union { unsigned u[4]; bf16x8 v; } cvp;
; #pragma unroll
;           for (int i = 0; i < 4; ++i) {
;             const float p0 = __builtin_amdgcn_exp2f(s[t2][hf * 8 + 2 * i] * cs - mnew);
;             const float p1 = __builtin_amdgcn_exp2f(s[t2][hf * 8 + 2 * i + 1] * cs - mnew);
;             psum += p0 + p1;
;             cvp.u[i] = pack2(p0, p1);
;           }
;           pf[t2 * 2 + hf] = cvp.v;
;         }
;       lrun += psum;
; #pragma unroll
;       for (int dt = 0; dt < 2; ++dt)
; #pragma unroll
;         for (int s4 = 0; s4 < 4; ++s4) {
;           const bf16x8 vfr = *(const bf16x8*)(Vs + (32 * dt + r) * 72 + 16 * s4 + 8 * hh);
;           oacc[dt] = __builtin_amdgcn_mfma_f32_32x32x16_bf16(vfr, pf[s4], oacc[dt], 0, 0, 0);
;         }
;     }
;     const float ltot = lrun + __shfl_xor(lrun, 32);
;     const float inv = 1.f / ltot;
;     bf16_t* op = p.hxc + xrow * 1024 + h * 64;
; #pragma unroll
;     for (int dt = 0; dt < 2; ++dt)
; #pragma unroll
;       for (int i4 = 0; i4 < 4; ++i4) {
;         const int d = 32 * dt + 8 * i4 + 4 * hh;
;         uint2 u; u.x = pack2(oacc[dt][4 * i4] * inv, oacc[dt][4 * i4 + 1] * inv); u.y = pack2(oacc[dt][4 * i4 + 2] * inv, oacc[dt][4 * i4 + 3] * inv);
;         *(uint2*)(op + d) = u;
;       }
;   }
.LBB0_2024:
	v_fma_f32 v3, v52, s25, -v147
	v_fma_f32 v52, v53, s25, -v147
	v_exp_f32_e32 v3, v3
	v_exp_f32_e32 v52, v52
	v_fma_f32 v36, v36, s25, -v147
	v_exp_f32_e32 v70, v36
	v_fma_f32 v36, v37, s25, -v147
	v_add_f32_e32 v53, v3, v52
	v_cvt_pk_bf16_f32 v52, v3, v52
	v_add_f32_e32 v3, 0, v53
	v_fma_f32 v53, v54, s25, -v147
	v_fma_f32 v54, v55, s25, -v147
	v_exp_f32_e32 v53, v53
	v_exp_f32_e32 v54, v54
	v_fma_f32 v55, v56, s25, -v147
	v_fma_f32 v56, v57, s25, -v147
	v_exp_f32_e32 v55, v55
	v_exp_f32_e32 v56, v56
	v_exp_f32_e32 v71, v36
	v_fma_f32 v36, v38, s25, -v147
	v_exp_f32_e32 v72, v36
	v_fma_f32 v36, v39, s25, -v147
	v_exp_f32_e32 v73, v36
	v_fma_f32 v36, v40, s25, -v147
	v_add_f32_e32 v57, v53, v54
	v_exp_f32_e32 v74, v36
	v_fma_f32 v36, v41, s25, -v147
	v_add_f32_e32 v3, v57, v3
	v_cvt_pk_bf16_f32 v53, v53, v54
	v_add_f32_e32 v54, v55, v56
	v_exp_f32_e32 v75, v36
	v_fma_f32 v36, v42, s25, -v147
	v_add_f32_e32 v3, v54, v3
	v_cvt_pk_bf16_f32 v54, v55, v56
	v_fma_f32 v55, v58, s25, -v147
	v_fma_f32 v56, v59, s25, -v147
	v_exp_f32_e32 v76, v36
	ds_read_b128 v[36:39], v146 offset:46080
	v_exp_f32_e32 v55, v55
	v_exp_f32_e32 v56, v56
	v_fma_f32 v57, v60, s25, -v147
	v_fma_f32 v58, v61, s25, -v147
	v_exp_f32_e32 v57, v57
	v_exp_f32_e32 v58, v58
	v_add_f32_e32 v59, v55, v56
	v_add_f32_e32 v3, v59, v3
	v_cvt_pk_bf16_f32 v55, v55, v56
	v_add_f32_e32 v56, v57, v58
	v_add_f32_e32 v3, v56, v3
	v_fma_f32 v56, v62, s25, -v147
	v_exp_f32_e32 v68, v56
	v_fma_f32 v56, v63, s25, -v147
	ds_read_b128 v[60:63], v146 offset:46112
	s_waitcnt lgkmcnt(1)
	v_mfma_f32_32x32x16_bf16 v[4:19], v[36:39], v[52:55], v[4:19]
	v_exp_f32_e32 v69, v56
	v_fma_f32 v56, v64, s25, -v147
	v_fma_f32 v36, v45, s25, -v147
	v_exp_f32_e32 v64, v56
	v_fma_f32 v56, v65, s25, -v147
	v_exp_f32_e32 v79, v36
	v_fma_f32 v36, v46, s25, -v147
	v_exp_f32_e32 v65, v56
	v_fma_f32 v56, v66, s25, -v147
	v_exp_f32_e32 v80, v36
	v_fma_f32 v36, v47, s25, -v147
	v_exp_f32_e32 v66, v56
	v_fma_f32 v56, v67, s25, -v147
	v_exp_f32_e32 v81, v36
	ds_read_b128 v[36:39], v146 offset:46144
	v_exp_f32_e32 v67, v56
	v_cvt_pk_bf16_f32 v56, v57, v58
	v_cvt_pk_bf16_f32 v57, v68, v69
	v_cvt_pk_bf16_f32 v58, v64, v65
	v_cvt_pk_bf16_f32 v59, v66, v67
	v_fma_f32 v44, v44, s25, -v147
	s_waitcnt lgkmcnt(1)
	v_mfma_f32_32x32x16_bf16 v[4:19], v[60:63], v[56:59], v[4:19]
	v_exp_f32_e32 v78, v44
	v_fma_f32 v44, v48, s25, -v147
	v_exp_f32_e32 v60, v44
	v_fma_f32 v44, v49, s25, -v147
	v_exp_f32_e32 v61, v44
	v_fma_f32 v44, v50, s25, -v147
	v_fma_f32 v40, v43, s25, -v147
	v_exp_f32_e32 v62, v44
	ds_read_b128 v[44:47], v146 offset:46176
	v_exp_f32_e32 v77, v40
	v_cvt_pk_bf16_f32 v40, v70, v71
	v_cvt_pk_bf16_f32 v41, v72, v73
	v_cvt_pk_bf16_f32 v42, v74, v75
	v_cvt_pk_bf16_f32 v43, v76, v77
	s_lshl_b32 s16, s16, 1
	s_waitcnt lgkmcnt(1)
	v_mfma_f32_32x32x16_bf16 v[4:19], v[36:39], v[40:43], v[4:19]
	v_fma_f32 v36, v51, s25, -v147
	ds_read_b128 v[48:51], v146 offset:50688
	v_exp_f32_e32 v63, v36
	v_cvt_pk_bf16_f32 v36, v78, v79
	v_cvt_pk_bf16_f32 v37, v80, v81
	v_cvt_pk_bf16_f32 v38, v60, v61
	v_cvt_pk_bf16_f32 v39, v62, v63
	s_add_i32 s3, s3, s54
	s_waitcnt lgkmcnt(1)
	v_mfma_f32_32x32x16_bf16 v[4:19], v[44:47], v[36:39], v[4:19]
	v_add_f32_e32 v44, v68, v69
	v_add_f32_e32 v3, v44, v3
	v_add_f32_e32 v44, v64, v65
	v_add_f32_e32 v3, v44, v3
	v_add_f32_e32 v44, v66, v67
	v_add_f32_e32 v3, v44, v3
	ds_read_b128 v[44:47], v146 offset:50720
	s_waitcnt lgkmcnt(1)
	v_mfma_f32_32x32x16_bf16 v[20:35], v[48:51], v[52:55], v[20:35]
	v_add_f32_e32 v48, v70, v71
	v_add_f32_e32 v3, v48, v3
	v_add_f32_e32 v48, v72, v73
	v_add_f32_e32 v3, v48, v3
	v_add_f32_e32 v48, v74, v75
	v_add_f32_e32 v3, v48, v3
	ds_read_b128 v[48:51], v146 offset:50752
	s_waitcnt lgkmcnt(1)
	v_mfma_f32_32x32x16_bf16 v[20:35], v[44:47], v[56:59], v[20:35]
	v_add_f32_e32 v44, v76, v77
	v_add_f32_e32 v3, v44, v3
	v_add_f32_e32 v52, v78, v79
	v_add_f32_e32 v53, v80, v81
	v_add_f32_e32 v3, v52, v3
	v_add_f32_e32 v54, v60, v61
	v_add_f32_e32 v3, v53, v3
	v_add_f32_e32 v55, v62, v63
	v_add_f32_e32 v3, v54, v3
	v_add_f32_e32 v3, v55, v3
	v_add_f32_e32 v3, v127, v3
	ds_read_b128 v[44:47], v146 offset:50784
	s_waitcnt lgkmcnt(1)
	v_mfma_f32_32x32x16_bf16 v[20:35], v[48:51], v[40:43], v[20:35]
	ds_bpermute_b32 v40, v125, v3
	v_mov_b32_e32 v127, v2
	s_cmpk_gt_i32 s3, 0x3ff
	s_waitcnt lgkmcnt(0)
	v_add_f32_e32 v3, v3, v40
	v_div_scale_f32 v40, s[12:13], v3, v3, 1.0
	v_rcp_f32_e32 v41, v40
	v_mfma_f32_32x32x16_bf16 v[20:35], v[44:47], v[36:39], v[20:35]
	v_fma_f32 v36, -v40, v41, 1.0
	v_fmac_f32_e32 v41, v36, v41
	v_div_scale_f32 v36, vcc, 1.0, v3, 1.0
	v_mul_f32_e32 v37, v36, v41
	v_fma_f32 v38, -v40, v37, v36
	v_fmac_f32_e32 v37, v38, v41
	v_fma_f32 v36, -v40, v37, v36
	v_div_fmas_f32 v36, v36, v41, v37
	v_div_fixup_f32 v3, v36, v3, 1.0
	v_lshlrev_b64 v[36:37], 11, v[128:129]
	v_lshl_add_u64 v[36:37], s[10:11], 0, v[36:37]
	v_mul_f32_e32 v4, v4, v3
	v_mul_f32_e32 v5, v5, v3
	v_lshl_add_u64 v[36:37], v[36:37], 0, s[16:17]
	v_cvt_pk_bf16_f32 v4, v4, v5
	v_mul_f32_e32 v5, v6, v3
	v_mul_f32_e32 v6, v7, v3
	v_cvt_pk_bf16_f32 v5, v5, v6
	v_lshl_add_u64 v[6:7], v[36:37], 0, v[126:127]
	global_store_dwordx2 v[6:7], v[4:5], off
	v_mul_f32_e32 v4, v8, v3
	v_mul_f32_e32 v5, v9, v3
	v_cvt_pk_bf16_f32 v4, v4, v5
	v_mul_f32_e32 v5, v10, v3
	v_mul_f32_e32 v8, v11, v3
	v_cvt_pk_bf16_f32 v5, v5, v8
	global_store_dwordx2 v[6:7], v[4:5], off offset:16
	v_mul_f32_e32 v4, v12, v3
	v_mul_f32_e32 v5, v13, v3
	v_cvt_pk_bf16_f32 v4, v4, v5
	v_mul_f32_e32 v5, v14, v3
	v_mul_f32_e32 v8, v15, v3
	v_cvt_pk_bf16_f32 v5, v5, v8
	global_store_dwordx2 v[6:7], v[4:5], off offset:32
	v_mul_f32_e32 v4, v16, v3
	v_mul_f32_e32 v5, v17, v3
	v_cvt_pk_bf16_f32 v4, v4, v5
	v_mul_f32_e32 v5, v18, v3
	v_mul_f32_e32 v8, v19, v3
	v_cvt_pk_bf16_f32 v5, v5, v8
	global_store_dwordx2 v[6:7], v[4:5], off offset:48
	v_mul_f32_e32 v4, v20, v3
	v_mul_f32_e32 v5, v21, v3
	v_cvt_pk_bf16_f32 v4, v4, v5
	v_mul_f32_e32 v5, v22, v3
	v_mul_f32_e32 v8, v23, v3
	v_cvt_pk_bf16_f32 v5, v5, v8
	global_store_dwordx2 v[6:7], v[4:5], off offset:64
	v_mul_f32_e32 v4, v24, v3
	v_mul_f32_e32 v5, v25, v3
	v_cvt_pk_bf16_f32 v4, v4, v5
	v_mul_f32_e32 v5, v26, v3
	v_mul_f32_e32 v8, v27, v3
	v_cvt_pk_bf16_f32 v5, v5, v8
	global_store_dwordx2 v[6:7], v[4:5], off offset:80
	v_mul_f32_e32 v4, v28, v3
	v_mul_f32_e32 v5, v29, v3
	v_cvt_pk_bf16_f32 v4, v4, v5
	v_mul_f32_e32 v5, v30, v3
	v_mul_f32_e32 v8, v31, v3
	v_cvt_pk_bf16_f32 v5, v5, v8
	global_store_dwordx2 v[6:7], v[4:5], off offset:96
	v_mul_f32_e32 v4, v32, v3
	v_mul_f32_e32 v5, v33, v3
	v_cvt_pk_bf16_f32 v4, v4, v5
	v_mul_f32_e32 v5, v34, v3
	v_mul_f32_e32 v3, v35, v3
	v_cvt_pk_bf16_f32 v5, v5, v3
	global_store_dwordx2 v[6:7], v[4:5], off offset:112
	s_cbranch_scc1 .LBB0_2039

; #define ATT_GLOAD(kt) do { \
;       rk0 = *(const uint4*)(kn_base + (size_t)((kt) * 64 + srow) * 1024 + sch * 8); \
;       rv0 = *(const uint4*)(vt_base + (size_t)srow * 2304 + (kt) * 64 + sch * 8); \
;       if (tid < 256) rp = *(const uint4*)(kpe_base + (size_t)((kt) * 64 + (tid >> 2)) * 32 + (tid & 3) * 8); } while (0)
; __device__ __forceinline__ void phase_attn(CP& p, char* smem, int vid0, int grid) {
;     ...
;     for (int kt = 0; kt < 36; ++kt) {
;       __syncthreads();
;       {
;         *(uint4*)(Ks + srow * 104 + sch * 8) = rk0;
;         uint2 lo, hi;
;         lo.x = rv0.x; lo.y = rv0.y; hi.x = rv0.z; hi.y = rv0.w;
;         *(uint2*)(Vs + srow * 72 + (sch >> 1) * 16 + (sch & 1) * 4) = lo; *(uint2*)(Vs + srow * 72 + (sch >> 1) * 16 + 8 + (sch & 1) * 4) = hi;
;       }
;       if (tid < 256) *(uint4*)(Ks + (tid >> 2) * 104 + 64 + (tid & 3) * 8) = rp;
;       __syncthreads();
;       if (kt + 1 < 36) ATT_GLOAD(kt + 1);
.Lattn_norescale_P:
.Lattn_body_B:
	v_add_u32_e32 v3, 0xb000, v139
	s_waitcnt vmcnt(1)
	ds_write_b128 v138, v[96:99] offset:32768
	s_waitcnt vmcnt(0)
	s_and_saveexec_b64 s[22:23], s[6:7]
	ds_write_b128 v140, v[100:103] offset:32896
	s_or_b64 exec, exec, s[22:23]
	s_waitcnt lgkmcnt(0)
	s_barrier
	ds_write2_b64 v3, v[92:93], v[94:95] offset0:128 offset1:130
	s_cmp_eq_u32 s12, 0x23000
	s_cbranch_scc1 .Lattn_nogl_B
	global_load_dwordx4 v[96:99], v[134:135], off
	global_load_dwordx4 v[92:95], v[132:133], off
	s_and_saveexec_b64 s[22:23], s[6:7]
	s_cbranch_execz .Lattn_nokpe_B
	v_lshl_add_u64 v[204:205], v[130:131], 0, s[12:13]
	v_add_co_u32_e32 v204, vcc, 0x1000, v204
	s_nop 1
	v_addc_co_u32_e32 v205, vcc, 0, v205, vcc
	global_load_dwordx4 v[100:103], v[204:205], off

; __device__ __forceinline__ unsigned pack2(float a, float b) { unsigned r; asm("v_cvt_pk_bf16_f32 %0, %1, %2" : "=v"(r) : "v"(a), "v"(b)); return r; }
; __device__ __forceinline__ void phase_attn(CP& p, char* smem, int vid0, int grid) {
;     ...
;       f32x16 s[2];
; #pragma unroll
;       for (int t2 = 0; t2 < 2; ++t2) {
; #pragma unroll
;         for (int i = 0; i < 16; ++i) s[t2][i] = 0.f;
; #pragma unroll
;         for (int kk = 0; kk < 6; ++kk) {
;           const bf16x8 a = *(const bf16x8*)(Ks + (32 * t2 + r) * 104 + 16 * kk + 8 * hh);
;           s[t2] = __builtin_amdgcn_mfma_f32_32x32x16_bf16(a, qf[kk], s[t2], 0, 0, 0);
;         }
;       }
;       float mx = s[0][0];
; #pragma unroll
;       for (int i = 1; i < 16; ++i) mx = fmaxf(mx, s[0][i]);
; #pragma unroll
;       for (int i = 0; i < 16; ++i) mx = fmaxf(mx, s[1][i]);
;       mx = fmaxf(mx, __shfl_xor(mx, 32));
;       const float mcand = mx * cs;
;       if (__builtin_amdgcn_ballot_w64(mcand > mrun + 6.0f) != 0ull) {
;         const float mnew_ = fmaxf(mrun, mcand);
;         const float alpha = __builtin_amdgcn_exp2f(mrun - mnew_);
;         mrun = mnew_;
;         lrun *= alpha;
; #pragma unroll
;         for (int i = 0; i < 16; ++i) { oacc[0][i] *= alpha; oacc[1][i] *= alpha; }
;       }
;       const float mnew = mrun;
;       float psum = 0.f;
;       bf16x8 pf[4];
; #pragma unroll
;       for (int t2 = 0; t2 < 2; ++t2)
; #pragma unroll
;         for (int hf = 0; hf < 2; ++hf) {
;           union { unsigned u[4]; bf16x8 v; } cvp;
; #pragma unroll
;           for (int i = 0; i < 4; ++i) {
;             const float p0 = __builtin_amdgcn_exp2f(s[t2][hf * 8 + 2 * i] * cs - mnew);
;             const float p1 = __builtin_amdgcn_exp2f(s[t2][hf * 8 + 2 * i + 1] * cs - mnew);
;             psum += p0 + p1;
;             cvp.u[i] = pack2(p0, p1);
;           }
;           pf[t2 * 2 + hf] = cvp.v;
;         }
;       lrun += psum;
; #pragma unroll
;       for (int dt = 0; dt < 2; ++dt)
; #pragma unroll
;         for (int s4 = 0; s4 < 4; ++s4) {
;           const bf16x8 vfr = *(const bf16x8*)(Vs + (32 * dt + r) * 72 + 16 * s4 + 8 * hh);
;           oacc[dt] = __builtin_amdgcn_mfma_f32_32x32x16_bf16(vfr, pf[s4], oacc[dt], 0, 0, 0);
;         }
.Lattn_nogl_B:
	ds_read_b128 v[204:207], v145 offset:32768
	ds_read_b128 v[208:211], v145 offset:32800
	ds_read_b128 v[212:215], v145 offset:32832
	ds_read_b128 v[216:219], v145 offset:32864
	ds_read_b128 v[220:223], v145 offset:32896
	ds_read_b128 v[224:227], v145 offset:32928
	ds_read_b128 v[228:231], v145 offset:39424
	ds_read_b128 v[232:235], v145 offset:39456
	ds_read_b128 v[236:239], v145 offset:39488
	ds_read_b128 v[240:243], v145 offset:39520
	ds_read_b128 v[244:247], v145 offset:39552
	ds_read_b128 v[252:255], v145 offset:39584
	v_fma_f32 v188, v188, s25, -v147
	v_exp_f32_e32 v164, v188
	v_fma_f32 v188, v189, s25, -v147
	v_exp_f32_e32 v165, v188
	v_fma_f32 v188, v190, s25, -v147
	v_exp_f32_e32 v166, v188
	s_waitcnt lgkmcnt(11)
	v_mfma_f32_32x32x16_bf16 v[52:67], v[204:207], v[72:75], 0
	v_fma_f32 v188, v191, s25, -v147
	v_exp_f32_e32 v167, v188
	v_fma_f32 v188, v192, s25, -v147
	v_fma_f32 v192, v196, s25, -v147
	v_exp_f32_e32 v149, v192
	v_fma_f32 v192, v197, s25, -v147
	s_waitcnt lgkmcnt(10)
	v_mfma_f32_32x32x16_bf16 v[52:67], v[208:211], v[68:71], v[52:67]
	v_exp_f32_e32 v151, v192
	v_fma_f32 v192, v198, s25, -v147
	v_exp_f32_e32 v148, v192
	v_fma_f32 v192, v199, s25, -v147
	v_exp_f32_e32 v150, v192
	v_fma_f32 v192, v200, s25, -v147
	s_waitcnt lgkmcnt(9)
	v_mfma_f32_32x32x16_bf16 v[52:67], v[212:215], v[80:83], v[52:67]
	v_exp_f32_e32 v153, v192
	v_fma_f32 v192, v201, s25, -v147
	v_exp_f32_e32 v201, v192
	v_fma_f32 v192, v202, s25, -v147
	v_fma_f32 v172, v172, s25, -v147
	v_exp_f32_e32 v152, v192
	s_waitcnt lgkmcnt(8)
	v_mfma_f32_32x32x16_bf16 v[52:67], v[216:219], v[76:79], v[52:67]
	v_fma_f32 v192, v203, s25, -v147
	v_exp_f32_e32 v203, v172
	v_fma_f32 v172, v173, s25, -v147
	v_exp_f32_e32 v155, v172
	v_fma_f32 v172, v174, s25, -v147
	v_exp_f32_e32 v202, v172
	s_waitcnt lgkmcnt(7)
	v_mfma_f32_32x32x16_bf16 v[52:67], v[220:223], v[84:87], v[52:67]
	v_fma_f32 v172, v175, s25, -v147
	v_exp_f32_e32 v154, v172
	v_fma_f32 v172, v176, s25, -v147
	v_exp_f32_e32 v157, v172
	v_fma_f32 v172, v177, s25, -v147
	v_exp_f32_e32 v159, v172
	s_waitcnt lgkmcnt(6)
	v_mfma_f32_32x32x16_bf16 v[52:67], v[224:227], v[88:91], v[52:67]
	v_fma_f32 v172, v178, s25, -v147
	v_exp_f32_e32 v156, v172
	s_waitcnt lgkmcnt(0)
	ds_read_b128 v[172:175], v146 offset:13312
	ds_read_b128 v[196:199], v146 offset:13344
	v_exp_f32_e32 v168, v188
	v_fma_f32 v188, v193, s25, -v147
	v_exp_f32_e32 v169, v188
	v_fma_f32 v188, v194, s25, -v147
	v_mfma_f32_32x32x16_bf16 v[36:51], v[228:231], v[72:75], 0
	v_exp_f32_e32 v170, v188
	v_fma_f32 v188, v195, s25, -v147
	v_exp_f32_e32 v171, v188
	v_cvt_pk_bf16_f32 v188, v164, v165
	v_cvt_pk_bf16_f32 v189, v166, v167
	v_cvt_pk_bf16_f32 v190, v168, v169
	v_cvt_pk_bf16_f32 v191, v170, v171
	v_exp_f32_e32 v200, v192
	s_waitcnt lgkmcnt(1)
	v_mfma_f32_32x32x16_bf16 v[4:19], v[172:175], v[188:191], v[4:19]
	v_fma_f32 v172, v181, s25, -v147
	v_exp_f32_e32 v163, v172
	v_fma_f32 v172, v182, s25, -v147
	v_exp_f32_e32 v160, v172
	v_mfma_f32_32x32x16_bf16 v[36:51], v[232:235], v[68:71], v[36:51]
	ds_read_b128 v[172:175], v146 offset:13376
	v_cvt_pk_bf16_f32 v192, v149, v151
	v_cvt_pk_bf16_f32 v193, v148, v150
	v_cvt_pk_bf16_f32 v194, v153, v201
	v_cvt_pk_bf16_f32 v195, v152, v200
	v_fma_f32 v180, v180, s25, -v147
	s_waitcnt lgkmcnt(1)
	v_mfma_f32_32x32x16_bf16 v[4:19], v[196:199], v[192:195], v[4:19]
	v_exp_f32_e32 v161, v180
	v_fma_f32 v180, v183, s25, -v147
	v_exp_f32_e32 v162, v180
	v_fma_f32 v180, v184, s25, -v147
	v_exp_f32_e32 v197, v180
	v_fma_f32 v180, v185, s25, -v147
	v_mfma_f32_32x32x16_bf16 v[36:51], v[236:239], v[80:83], v[36:51]
	v_fma_f32 v176, v179, s25, -v147
	v_exp_f32_e32 v199, v180
	ds_read_b128 v[180:183], v146 offset:13408
	v_exp_f32_e32 v158, v176
	v_cvt_pk_bf16_f32 v176, v203, v155
	v_cvt_pk_bf16_f32 v177, v202, v154
	v_cvt_pk_bf16_f32 v178, v157, v159
	v_cvt_pk_bf16_f32 v179, v156, v158
	v_fma_f32 v184, v186, s25, -v147
	s_waitcnt lgkmcnt(1)
	v_mfma_f32_32x32x16_bf16 v[4:19], v[172:175], v[176:179], v[4:19]
	v_fma_f32 v172, v187, s25, -v147
	v_exp_f32_e32 v196, v184
	v_exp_f32_e32 v198, v172
	v_mfma_f32_32x32x16_bf16 v[36:51], v[240:243], v[76:79], v[36:51]
	v_cvt_pk_bf16_f32 v172, v161, v163
	v_cvt_pk_bf16_f32 v173, v160, v162
	v_cvt_pk_bf16_f32 v174, v197, v199
	v_cvt_pk_bf16_f32 v175, v196, v198
	v_add_f32_e32 v184, v164, v165
	s_waitcnt lgkmcnt(0)
; __device__ __forceinline__ unsigned pack2(float a, float b) { unsigned r; asm("v_cvt_pk_bf16_f32 %0, %1, %2" : "=v"(r) : "v"(a), "v"(b)); return r; }
; __device__ __forceinline__ void phase_attn(CP& p, char* smem, int vid0, int grid) {
;     ...
;       float mx = s[0][0];
; #pragma unroll
;       for (int i = 1; i < 16; ++i) mx = fmaxf(mx, s[0][i]);
; #pragma unroll
;       for (int i = 0; i < 16; ++i) mx = fmaxf(mx, s[1][i]);
;       mx = fmaxf(mx, __shfl_xor(mx, 32));
;       const float mcand = mx * cs;
;       if (__builtin_amdgcn_ballot_w64(mcand > mrun + 6.0f) != 0ull) {
;         const float mnew_ = fmaxf(mrun, mcand);
;         const float alpha = __builtin_amdgcn_exp2f(mrun - mnew_);
;         mrun = mnew_;
;         lrun *= alpha;
; #pragma unroll
;         for (int i = 0; i < 16; ++i) { oacc[0][i] *= alpha; oacc[1][i] *= alpha; }
;       }
;       const float mnew = mrun;
;       float psum = 0.f;
;       bf16x8 pf[4];
; #pragma unroll
;       for (int t2 = 0; t2 < 2; ++t2)
; #pragma unroll
;         for (int hf = 0; hf < 2; ++hf) {
;           union { unsigned u[4]; bf16x8 v; } cvp;
; #pragma unroll
;           for (int i = 0; i < 4; ++i) {
;             const float p0 = __builtin_amdgcn_exp2f(s[t2][hf * 8 + 2 * i] * cs - mnew);
;             const float p1 = __builtin_amdgcn_exp2f(s[t2][hf * 8 + 2 * i + 1] * cs - mnew);
;             psum += p0 + p1;
;             cvp.u[i] = pack2(p0, p1);
;           }
;           pf[t2 * 2 + hf] = cvp.v;
;         }
;       lrun += psum;
; #pragma unroll
;       for (int dt = 0; dt < 2; ++dt)
; #pragma unroll
;         for (int s4 = 0; s4 < 4; ++s4) {
;           const bf16x8 vfr = *(const bf16x8*)(Vs + (32 * dt + r) * 72 + 16 * s4 + 8 * hh);
;           oacc[dt] = __builtin_amdgcn_mfma_f32_32x32x16_bf16(vfr, pf[s4], oacc[dt], 0, 0, 0);
;         }
	v_mfma_f32_32x32x16_bf16 v[4:19], v[180:183], v[172:175], v[4:19]
	ds_read_b128 v[180:183], v146 offset:17920
	v_add_f32_e32 v164, 0, v184
	ds_read_b128 v[184:187], v146 offset:17952
	v_add_f32_e32 v165, v166, v167
	s_add_u32 s12, s12, 0x1000
	s_addc_u32 s13, s13, 0
	v_lshl_add_u64 v[132:133], v[132:133], 0, s[18:19]
	s_waitcnt lgkmcnt(1)
	v_mfma_f32_32x32x16_bf16 v[20:35], v[180:183], v[188:191], v[20:35]
	v_add_f32_e32 v180, v165, v164
	v_add_f32_e32 v181, v168, v169
	v_mfma_f32_32x32x16_bf16 v[36:51], v[244:247], v[84:87], v[36:51]
	v_add_f32_e32 v180, v181, v180
	v_add_f32_e32 v181, v170, v171
	v_add_f32_e32 v190, v181, v180
	ds_read_b128 v[180:183], v146 offset:17984
	v_pk_add_f32 v[188:189], v[148:149], v[150:151]
	s_waitcnt lgkmcnt(1)
	v_mfma_f32_32x32x16_bf16 v[20:35], v[184:187], v[192:195], v[20:35]
	v_add_f32_e32 v184, v189, v190
	v_add_f32_e32 v186, v188, v184
	v_add_f32_e64 v184, v152, v200
	v_add_f32_e64 v185, v153, v201
	v_add_f32_e64 v188, v202, v154
	v_mfma_f32_32x32x16_bf16 v[36:51], v[252:255], v[88:91], v[36:51]
	v_add_f32_e64 v189, v203, v155
	v_add_f32_e32 v185, v185, v186
	v_add_f32_e32 v190, v184, v185
	ds_read_b128 v[184:187], v146 offset:18016
	s_waitcnt lgkmcnt(1)
	v_mfma_f32_32x32x16_bf16 v[20:35], v[180:183], v[176:179], v[20:35]
	v_add_f32_e32 v176, v189, v190
	v_add_f32_e32 v178, v188, v176
	v_add_f32_e64 v176, v156, v158
	v_add_f32_e64 v177, v157, v159
	v_add_f32_e32 v177, v177, v178
	v_add_f32_e32 v180, v176, v177
	v_pk_add_f32 v[176:177], v[160:161], v[162:163]
	s_waitcnt lgkmcnt(0)
	v_mfma_f32_32x32x16_bf16 v[20:35], v[184:187], v[172:175], v[20:35]
	v_add_f32_e32 v172, v177, v180
	v_add_f32_e64 v178, v196, v198
	v_add_f32_e64 v179, v197, v199
	v_add_f32_e32 v172, v176, v172
	v_add_f32_e32 v172, v179, v172
	v_add_f32_e32 v172, v178, v172
	v_add_f32_e32 v127, v127, v172
	v_lshl_add_u64 v[134:135], v[134:135], 0, s[20:21]
	v_max_f32_e32 v156, v53, v53
	v_max_f32_e32 v157, v52, v52
	v_max_f32_e32 v156, v157, v156
	v_max3_f32 v148, v156, v54, v55
	v_max3_f32 v148, v148, v56, v57
	v_max3_f32 v148, v148, v58, v59
	v_max3_f32 v148, v148, v60, v61
	v_max3_f32 v148, v148, v62, v63
	v_max3_f32 v148, v148, v64, v65
	v_max3_f32 v148, v148, v66, v67
	v_max3_f32 v148, v148, v36, v37
	v_max3_f32 v148, v148, v38, v39
	v_max3_f32 v148, v148, v40, v41
	v_max3_f32 v148, v148, v42, v43
	v_max3_f32 v148, v148, v44, v45
	v_max3_f32 v148, v148, v46, v47
	v_max3_f32 v148, v148, v48, v49
	v_max3_f32 v148, v148, v50, v51
	ds_bpermute_b32 v149, v125, v148
	s_waitcnt lgkmcnt(0)
	v_max_f32_e32 v149, v149, v149
	v_max_f32_e32 v148, v148, v149
	v_mul_f32_e32 v148, 0x3e16c740, v148
	v_add_f32_e32 v149, 0x40c00000, v147
	v_cmp_gt_f32_e32 vcc, v148, v149
	s_cbranch_vccz .Lattn_norescale_B
	v_max_f32_e32 v148, v148, v148
	v_max_f32_e32 v149, v147, v147
	v_max_f32_e32 v149, v149, v148
	v_sub_f32_e32 v147, v147, v149
	v_exp_f32_e32 v148, v147
	v_mov_b32_e32 v147, v149
	v_pk_mul_f32 v[34:35], v[34:35], v[148:149] op_sel_hi:[1,0]
	v_pk_mul_f32 v[32:33], v[32:33], v[148:149] op_sel_hi:[1,0]
	v_pk_mul_f32 v[30:31], v[30:31], v[148:149] op_sel_hi:[1,0]
	v_pk_mul_f32 v[28:29], v[28:29], v[148:149] op_sel_hi:[1,0]
	v_pk_mul_f32 v[26:27], v[26:27], v[148:149] op_sel_hi:[1,0]
	v_pk_mul_f32 v[24:25], v[24:25], v[148:149] op_sel_hi:[1,0]
	v_pk_mul_f32 v[22:23], v[22:23], v[148:149] op_sel_hi:[1,0]
	v_pk_mul_f32 v[20:21], v[20:21], v[148:149] op_sel_hi:[1,0]
	v_pk_mul_f32 v[18:19], v[18:19], v[148:149] op_sel_hi:[1,0]
	v_pk_mul_f32 v[16:17], v[16:17], v[148:149] op_sel_hi:[1,0]
	v_pk_mul_f32 v[14:15], v[14:15], v[148:149] op_sel_hi:[1,0]
	v_pk_mul_f32 v[12:13], v[12:13], v[148:149] op_sel_hi:[1,0]
	v_pk_mul_f32 v[10:11], v[10:11], v[148:149] op_sel_hi:[1,0]
	v_pk_mul_f32 v[8:9], v[8:9], v[148:149] op_sel_hi:[1,0]
	v_pk_mul_f32 v[6:7], v[6:7], v[148:149] op_sel_hi:[1,0]
	v_pk_mul_f32 v[4:5], v[4:5], v[148:149] op_sel_hi:[1,0]
	v_mul_f32_e32 v127, v127, v148
.Lattn_norescale_B:
	s_cmp_eq_u32 s12, 0x24000
	s_cbranch_scc1 .Lattn_tail

; __device__ __forceinline__ unsigned pack2(float a, float b) { unsigned r; asm("v_cvt_pk_bf16_f32 %0, %1, %2" : "=v"(r) : "v"(a), "v"(b)); return r; }
; __device__ __forceinline__ void phase_attn(CP& p, char* smem, int vid0, int grid) {
;     ...
;       f32x16 s[2];
; #pragma unroll
;       for (int t2 = 0; t2 < 2; ++t2) {
; #pragma unroll
;         for (int i = 0; i < 16; ++i) s[t2][i] = 0.f;
; #pragma unroll
;         for (int kk = 0; kk < 6; ++kk) {
;           const bf16x8 a = *(const bf16x8*)(Ks + (32 * t2 + r) * 104 + 16 * kk + 8 * hh);
;           s[t2] = __builtin_amdgcn_mfma_f32_32x32x16_bf16(a, qf[kk], s[t2], 0, 0, 0);
;         }
;       }
;       float mx = s[0][0];
; #pragma unroll
;       for (int i = 1; i < 16; ++i) mx = fmaxf(mx, s[0][i]);
; #pragma unroll
;       for (int i = 0; i < 16; ++i) mx = fmaxf(mx, s[1][i]);
;       mx = fmaxf(mx, __shfl_xor(mx, 32));
;       const float mcand = mx * cs;
;       if (__builtin_amdgcn_ballot_w64(mcand > mrun + 6.0f) != 0ull) {
;         const float mnew_ = fmaxf(mrun, mcand);
;         const float alpha = __builtin_amdgcn_exp2f(mrun - mnew_);
;         mrun = mnew_;
;         lrun *= alpha;
; #pragma unroll
;         for (int i = 0; i < 16; ++i) { oacc[0][i] *= alpha; oacc[1][i] *= alpha; }
;       }
;       const float mnew = mrun;
;       float psum = 0.f;
;       bf16x8 pf[4];
; #pragma unroll
;       for (int t2 = 0; t2 < 2; ++t2)
; #pragma unroll
;         for (int hf = 0; hf < 2; ++hf) {
;           union { unsigned u[4]; bf16x8 v; } cvp;
; #pragma unroll
;           for (int i = 0; i < 4; ++i) {
;             const float p0 = __builtin_amdgcn_exp2f(s[t2][hf * 8 + 2 * i] * cs - mnew);
;             const float p1 = __builtin_amdgcn_exp2f(s[t2][hf * 8 + 2 * i + 1] * cs - mnew);
;             psum += p0 + p1;
;             cvp.u[i] = pack2(p0, p1);
;           }
;           pf[t2 * 2 + hf] = cvp.v;
;         }
;       lrun += psum;
; #pragma unroll
;       for (int dt = 0; dt < 2; ++dt)
; #pragma unroll
;         for (int s4 = 0; s4 < 4; ++s4) {
;           const bf16x8 vfr = *(const bf16x8*)(Vs + (32 * dt + r) * 72 + 16 * s4 + 8 * hh);
;           oacc[dt] = __builtin_amdgcn_mfma_f32_32x32x16_bf16(vfr, pf[s4], oacc[dt], 0, 0, 0);
;         }
.Lattn_nogl_A:
	ds_read_b128 v[204:207], v145
	ds_read_b128 v[208:211], v145 offset:32
	ds_read_b128 v[212:215], v145 offset:64
	ds_read_b128 v[216:219], v145 offset:96
	ds_read_b128 v[220:223], v145 offset:128
	ds_read_b128 v[224:227], v145 offset:160
	ds_read_b128 v[228:231], v145 offset:6656
	ds_read_b128 v[232:235], v145 offset:6688
	ds_read_b128 v[236:239], v145 offset:6720
	ds_read_b128 v[240:243], v145 offset:6752
	ds_read_b128 v[244:247], v145 offset:6784
	ds_read_b128 v[252:255], v145 offset:6816
	v_fma_f32 v52, v52, s25, -v147
	v_exp_f32_e32 v164, v52
	v_fma_f32 v52, v53, s25, -v147
	v_exp_f32_e32 v165, v52
	v_fma_f32 v52, v54, s25, -v147
	v_exp_f32_e32 v166, v52
	s_waitcnt lgkmcnt(11)
	v_mfma_f32_32x32x16_bf16 v[188:203], v[204:207], v[72:75], 0
	v_fma_f32 v52, v55, s25, -v147
	v_exp_f32_e32 v167, v52
	v_fma_f32 v52, v56, s25, -v147
	v_fma_f32 v56, v60, s25, -v147
	v_exp_f32_e32 v149, v56
	v_fma_f32 v56, v61, s25, -v147
	s_waitcnt lgkmcnt(10)
	v_mfma_f32_32x32x16_bf16 v[188:203], v[208:211], v[68:71], v[188:203]
	v_exp_f32_e32 v151, v56
	v_fma_f32 v56, v62, s25, -v147
	v_exp_f32_e32 v148, v56
	v_fma_f32 v56, v63, s25, -v147
	v_exp_f32_e32 v150, v56
	v_fma_f32 v56, v64, s25, -v147
	s_waitcnt lgkmcnt(9)
	v_mfma_f32_32x32x16_bf16 v[188:203], v[212:215], v[80:83], v[188:203]
	v_exp_f32_e32 v153, v56
	v_fma_f32 v56, v65, s25, -v147
	v_exp_f32_e32 v65, v56
	v_fma_f32 v56, v66, s25, -v147
	v_fma_f32 v36, v36, s25, -v147
	v_exp_f32_e32 v152, v56
	s_waitcnt lgkmcnt(8)
	v_mfma_f32_32x32x16_bf16 v[188:203], v[216:219], v[76:79], v[188:203]
	v_fma_f32 v56, v67, s25, -v147
	v_exp_f32_e32 v67, v36
	v_fma_f32 v36, v37, s25, -v147
	v_exp_f32_e32 v155, v36
	v_fma_f32 v36, v38, s25, -v147
	v_exp_f32_e32 v66, v36
	s_waitcnt lgkmcnt(7)
	v_mfma_f32_32x32x16_bf16 v[188:203], v[220:223], v[84:87], v[188:203]
	v_fma_f32 v36, v39, s25, -v147
	v_exp_f32_e32 v154, v36
	v_fma_f32 v36, v40, s25, -v147
	v_exp_f32_e32 v157, v36
	v_fma_f32 v36, v41, s25, -v147
	v_exp_f32_e32 v159, v36
	s_waitcnt lgkmcnt(6)
	v_mfma_f32_32x32x16_bf16 v[188:203], v[224:227], v[88:91], v[188:203]
	v_fma_f32 v36, v42, s25, -v147
	v_exp_f32_e32 v156, v36
	s_waitcnt lgkmcnt(0)
	ds_read_b128 v[36:39], v146 offset:46080
	ds_read_b128 v[60:63], v146 offset:46112
	v_exp_f32_e32 v168, v52
	v_fma_f32 v52, v57, s25, -v147
	v_exp_f32_e32 v169, v52
	v_fma_f32 v52, v58, s25, -v147
	v_mfma_f32_32x32x16_bf16 v[172:187], v[228:231], v[72:75], 0
	v_exp_f32_e32 v170, v52
	v_fma_f32 v52, v59, s25, -v147
	v_exp_f32_e32 v171, v52
	v_cvt_pk_bf16_f32 v52, v164, v165
	v_cvt_pk_bf16_f32 v53, v166, v167
	v_cvt_pk_bf16_f32 v54, v168, v169
	v_cvt_pk_bf16_f32 v55, v170, v171
	v_exp_f32_e32 v64, v56
	s_waitcnt lgkmcnt(1)
	v_mfma_f32_32x32x16_bf16 v[4:19], v[36:39], v[52:55], v[4:19]
	v_fma_f32 v36, v45, s25, -v147
	v_exp_f32_e32 v163, v36
	v_fma_f32 v36, v46, s25, -v147
	v_exp_f32_e32 v160, v36
	v_mfma_f32_32x32x16_bf16 v[172:187], v[232:235], v[68:71], v[172:187]
	ds_read_b128 v[36:39], v146 offset:46144
	v_cvt_pk_bf16_f32 v56, v149, v151
	v_cvt_pk_bf16_f32 v57, v148, v150
	v_cvt_pk_bf16_f32 v58, v153, v65
	v_cvt_pk_bf16_f32 v59, v152, v64
	v_fma_f32 v44, v44, s25, -v147
	s_waitcnt lgkmcnt(1)
	v_mfma_f32_32x32x16_bf16 v[4:19], v[60:63], v[56:59], v[4:19]
	v_exp_f32_e32 v161, v44
	v_fma_f32 v44, v47, s25, -v147
	v_exp_f32_e32 v162, v44
	v_fma_f32 v44, v48, s25, -v147
	v_exp_f32_e32 v61, v44
	v_fma_f32 v44, v49, s25, -v147
	v_mfma_f32_32x32x16_bf16 v[172:187], v[236:239], v[80:83], v[172:187]
	v_fma_f32 v40, v43, s25, -v147
	v_exp_f32_e32 v63, v44
	ds_read_b128 v[44:47], v146 offset:46176
	v_exp_f32_e32 v158, v40
	v_cvt_pk_bf16_f32 v40, v67, v155
	v_cvt_pk_bf16_f32 v41, v66, v154
	v_cvt_pk_bf16_f32 v42, v157, v159
	v_cvt_pk_bf16_f32 v43, v156, v158
	v_fma_f32 v48, v50, s25, -v147
	s_waitcnt lgkmcnt(1)
	v_mfma_f32_32x32x16_bf16 v[4:19], v[36:39], v[40:43], v[4:19]
	v_fma_f32 v36, v51, s25, -v147
	v_exp_f32_e32 v60, v48
	v_exp_f32_e32 v62, v36
	v_mfma_f32_32x32x16_bf16 v[172:187], v[240:243], v[76:79], v[172:187]
	v_cvt_pk_bf16_f32 v36, v161, v163
	v_cvt_pk_bf16_f32 v37, v160, v162
	v_cvt_pk_bf16_f32 v38, v61, v63
	v_cvt_pk_bf16_f32 v39, v60, v62
	v_add_f32_e32 v48, v164, v165
	s_waitcnt lgkmcnt(0)
	v_mfma_f32_32x32x16_bf16 v[4:19], v[44:47], v[36:39], v[4:19]
	ds_read_b128 v[44:47], v146 offset:50688
	v_add_f32_e32 v164, 0, v48
	ds_read_b128 v[48:51], v146 offset:50720
	v_add_f32_e32 v165, v166, v167
	s_add_u32 s12, s12, 0x1000
	s_addc_u32 s13, s13, 0
	v_lshl_add_u64 v[132:133], v[132:133], 0, s[18:19]
	s_waitcnt lgkmcnt(1)
	v_mfma_f32_32x32x16_bf16 v[20:35], v[44:47], v[52:55], v[20:35]
	v_add_f32_e32 v44, v165, v164
	v_add_f32_e32 v45, v168, v169
	v_mfma_f32_32x32x16_bf16 v[172:187], v[244:247], v[84:87], v[172:187]
	v_add_f32_e32 v44, v45, v44
	v_add_f32_e32 v45, v170, v171
	v_add_f32_e32 v54, v45, v44
	ds_read_b128 v[44:47], v146 offset:50752
	v_pk_add_f32 v[52:53], v[148:149], v[150:151]
	s_waitcnt lgkmcnt(1)
	v_mfma_f32_32x32x16_bf16 v[20:35], v[48:51], v[56:59], v[20:35]
	v_add_f32_e32 v48, v53, v54
	v_add_f32_e32 v50, v52, v48
	v_add_f32_e64 v48, v152, v64
	v_add_f32_e64 v49, v153, v65
	v_add_f32_e64 v52, v66, v154
	v_mfma_f32_32x32x16_bf16 v[172:187], v[252:255], v[88:91], v[172:187]
	v_add_f32_e64 v53, v67, v155
	v_add_f32_e32 v49, v49, v50
	v_add_f32_e32 v54, v48, v49
	ds_read_b128 v[48:51], v146 offset:50784
	s_waitcnt lgkmcnt(1)
	v_mfma_f32_32x32x16_bf16 v[20:35], v[44:47], v[40:43], v[20:35]
	v_add_f32_e32 v40, v53, v54
	v_add_f32_e32 v42, v52, v40
	v_add_f32_e64 v40, v156, v158
	v_add_f32_e64 v41, v157, v159
	v_add_f32_e32 v41, v41, v42
	v_add_f32_e32 v44, v40, v41
	v_pk_add_f32 v[40:41], v[160:161], v[162:163]
	s_waitcnt lgkmcnt(0)
	v_mfma_f32_32x32x16_bf16 v[20:35], v[48:51], v[36:39], v[20:35]
	v_add_f32_e32 v36, v41, v44
	v_add_f32_e64 v42, v60, v62
	v_add_f32_e64 v43, v61, v63
	v_add_f32_e32 v36, v40, v36
	v_add_f32_e32 v36, v43, v36
	v_add_f32_e32 v36, v42, v36
	v_add_f32_e32 v127, v127, v36
	v_lshl_add_u64 v[134:135], v[134:135], 0, s[20:21]
	v_max_f32_e32 v156, v189, v189
	v_max_f32_e32 v157, v188, v188
	v_max_f32_e32 v156, v157, v156
	v_max3_f32 v148, v156, v190, v191
	v_max3_f32 v148, v148, v192, v193
	v_max3_f32 v148, v148, v194, v195
	v_max3_f32 v148, v148, v196, v197
	v_max3_f32 v148, v148, v198, v199
	v_max3_f32 v148, v148, v200, v201
	v_max3_f32 v148, v148, v202, v203
	v_max3_f32 v148, v148, v172, v173
	v_max3_f32 v148, v148, v174, v175
	v_max3_f32 v148, v148, v176, v177
	v_max3_f32 v148, v148, v178, v179
	v_max3_f32 v148, v148, v180, v181
	v_max3_f32 v148, v148, v182, v183
	v_max3_f32 v148, v148, v184, v185
	v_max3_f32 v148, v148, v186, v187
	ds_bpermute_b32 v149, v125, v148
	s_waitcnt lgkmcnt(0)
	v_max_f32_e32 v149, v149, v149
	v_max_f32_e32 v148, v148, v149
	v_mul_f32_e32 v148, 0x3e16c740, v148
	v_add_f32_e32 v149, 0x40c00000, v147
	v_cmp_gt_f32_e32 vcc, v148, v149
	s_cbranch_vccz .Lattn_norescale_A
; __device__ __forceinline__ void phase_attn(CP& p, char* smem, int vid0, int grid) {
;     ...
;       if (__builtin_amdgcn_ballot_w64(mcand > mrun + 6.0f) != 0ull) {
;         const float mnew_ = fmaxf(mrun, mcand);
;         const float alpha = __builtin_amdgcn_exp2f(mrun - mnew_);
;         mrun = mnew_;
;         lrun *= alpha;
; #pragma unroll
;         for (int i = 0; i < 16; ++i) { oacc[0][i] *= alpha; oacc[1][i] *= alpha; }
;       }
	v_max_f32_e32 v148, v148, v148
	v_max_f32_e32 v149, v147, v147
	v_max_f32_e32 v149, v149, v148
	v_sub_f32_e32 v147, v147, v149
	v_exp_f32_e32 v148, v147
	v_mov_b32_e32 v147, v149
	v_pk_mul_f32 v[34:35], v[34:35], v[148:149] op_sel_hi:[1,0]
	v_pk_mul_f32 v[32:33], v[32:33], v[148:149] op_sel_hi:[1,0]
	v_pk_mul_f32 v[30:31], v[30:31], v[148:149] op_sel_hi:[1,0]
	v_pk_mul_f32 v[28:29], v[28:29], v[148:149] op_sel_hi:[1,0]
	v_pk_mul_f32 v[26:27], v[26:27], v[148:149] op_sel_hi:[1,0]
	v_pk_mul_f32 v[24:25], v[24:25], v[148:149] op_sel_hi:[1,0]
	v_pk_mul_f32 v[22:23], v[22:23], v[148:149] op_sel_hi:[1,0]
	v_pk_mul_f32 v[20:21], v[20:21], v[148:149] op_sel_hi:[1,0]
	v_pk_mul_f32 v[18:19], v[18:19], v[148:149] op_sel_hi:[1,0]
	v_pk_mul_f32 v[16:17], v[16:17], v[148:149] op_sel_hi:[1,0]
	v_pk_mul_f32 v[14:15], v[14:15], v[148:149] op_sel_hi:[1,0]
	v_pk_mul_f32 v[12:13], v[12:13], v[148:149] op_sel_hi:[1,0]
	v_pk_mul_f32 v[10:11], v[10:11], v[148:149] op_sel_hi:[1,0]
	v_pk_mul_f32 v[8:9], v[8:9], v[148:149] op_sel_hi:[1,0]
	v_pk_mul_f32 v[6:7], v[6:7], v[148:149] op_sel_hi:[1,0]
	v_pk_mul_f32 v[4:5], v[4:5], v[148:149] op_sel_hi:[1,0]
	v_mul_f32_e32 v127, v127, v148
.Lattn_norescale_A:
	s_branch .Lattn_body_B
.Lattn_tail:
	s_branch .LBB0_2024
